# ln2: per-token expert loop uses v_readlane + scalar branch instead of 16 ds_bpermute round trips
# baseline (speedup 1.0000x reference)
.LBB0_1400:
	v_readlane_b32 s2, v76, s7
	s_cmp_lt_i32 s2, 0
	s_cbranch_scc1 .Lln2_next
	v_mov_b32_e32 v40, s2
	v_lshlrev_b64 v[78:79], 10, v[40:41]
	v_lshl_add_u64 v[78:79], v[36:37], 0, v[78:79]
	global_load_dword v40, v[78:79], off
	global_load_dword v85, v[78:79], off offset:256
	global_load_dword v87, v[78:79], off offset:512
	global_load_dword v89, v[78:79], off offset:768
	s_waitcnt vmcnt(3)
	v_cvt_f32_fp8_e32 v78, v40
	v_cvt_f32_fp8_sdwa v79, v40 src0_sel:BYTE_1
	v_cvt_f32_fp8_sdwa v80, v40 src0_sel:BYTE_2
	v_cvt_f32_fp8_sdwa v81, v40 src0_sel:BYTE_3
	s_waitcnt vmcnt(2)
	v_cvt_f32_fp8_e32 v82, v85
	v_cvt_f32_fp8_sdwa v83, v85 src0_sel:BYTE_1
	v_cvt_f32_fp8_sdwa v84, v85 src0_sel:BYTE_2
	v_cvt_f32_fp8_sdwa v85, v85 src0_sel:BYTE_3
	s_waitcnt vmcnt(1)
	v_cvt_f32_fp8_e32 v86, v87
	v_cvt_f32_fp8_sdwa v88, v87 src0_sel:BYTE_2
	s_waitcnt vmcnt(0)
	v_cvt_f32_fp8_e32 v90, v89
	v_cvt_f32_fp8_sdwa v92, v89 src0_sel:BYTE_2
	v_cvt_f32_fp8_sdwa v93, v89 src0_sel:BYTE_3
	v_cvt_f32_fp8_sdwa v91, v89 src0_sel:BYTE_1
	v_cvt_f32_fp8_sdwa v89, v87 src0_sel:BYTE_3
	v_cvt_f32_fp8_sdwa v87, v87 src0_sel:BYTE_1
	v_pk_fma_f32 v[52:53], v[92:93], s[6:7], v[52:53] op_sel_hi:[1,0,1]
	v_pk_fma_f32 v[50:51], v[90:91], s[6:7], v[50:51] op_sel_hi:[1,0,1]
	v_pk_fma_f32 v[54:55], v[88:89], s[6:7], v[54:55] op_sel_hi:[1,0,1]
	v_pk_fma_f32 v[56:57], v[86:87], s[6:7], v[56:57] op_sel_hi:[1,0,1]
	v_pk_fma_f32 v[58:59], v[84:85], s[6:7], v[58:59] op_sel_hi:[1,0,1]
	v_pk_fma_f32 v[60:61], v[82:83], s[6:7], v[60:61] op_sel_hi:[1,0,1]
	v_pk_fma_f32 v[62:63], v[80:81], s[6:7], v[62:63] op_sel_hi:[1,0,1]
	v_pk_fma_f32 v[64:65], v[78:79], s[6:7], v[64:65] op_sel_hi:[1,0,1]
.Lln2_next:
	s_add_i32 s7, s7, 1
	s_cmp_eq_u32 s7, 16
	s_cbranch_scc0 .LBB0_1400
	s_branch .LBB0_1393
